# speedup vs baseline: 1.0077x; 1.0012x over previous
; __device__ __forceinline__ unsigned pack2(float a, float b) { return (unsigned)f2bf(a) | ((unsigned)f2bf(b) << 16); }
; __device__ void phase_peer(const Params& p, int l, float* xout, char* smem) {
;     ...
; #pragma unroll
;     for (int i = 0; i < 4; ++i) {
;       int c0 = lane * 32 + i * 8;
;       float o[8];
; #pragma unroll
;       for (int j = 0; j < 8; ++j) o[j] = (y[i * 8 + j] - mu) * rstd * g2[c0 + j] + b2[c0 + j];
;       if (xout) {
;         float* op = xout + (long)t * D_ + c0;
;         *(float4*)op = make_float4(o[0], o[1], o[2], o[3]);
;         *(float4*)(op + 4) = make_float4(o[4], o[5], o[6], o[7]);
;       }
;       uint4 pk; pk.x = pack2(o[0], o[1]); pk.y = pack2(o[2], o[3]); pk.z = pack2(o[4], o[5]); pk.w = pack2(o[6], o[7]);
;       *(uint4*)(p.xb + (long)t * D_ + c0) = pk;
;     }
.LBB0_1257:
	v_and_b32_sdwa v8, v11, v209 dst_sel:DWORD dst_unused:UNUSED_PAD src0_sel:WORD_1 src1_sel:DWORD
	v_and_b32_sdwa v9, v10, v209 dst_sel:DWORD dst_unused:UNUSED_PAD src0_sel:WORD_1 src1_sel:DWORD
	v_and_b32_sdwa v0, v13, v209 dst_sel:DWORD dst_unused:UNUSED_PAD src0_sel:WORD_1 src1_sel:DWORD
	v_and_b32_sdwa v1, v12, v209 dst_sel:DWORD dst_unused:UNUSED_PAD src0_sel:WORD_1 src1_sel:DWORD
	v_add3_u32 v8, v11, v8, s65
	v_add3_u32 v9, v10, v9, s65
	v_add3_u32 v1, v12, v1, s65
	v_add3_u32 v0, v13, v0, s65
	v_and_b32_e32 v8, 0xffff0000, v8
	v_and_b32_e32 v10, 0xffff0000, v9
	v_or_b32_sdwa v9, v8, v0 dst_sel:DWORD dst_unused:UNUSED_PAD src0_sel:DWORD src1_sel:WORD_1
	v_or_b32_sdwa v8, v10, v1 dst_sel:DWORD dst_unused:UNUSED_PAD src0_sel:DWORD src1_sel:WORD_1
	v_and_b32_sdwa v0, v7, v209 dst_sel:DWORD dst_unused:UNUSED_PAD src0_sel:WORD_1 src1_sel:DWORD
	v_and_b32_sdwa v1, v6, v209 dst_sel:DWORD dst_unused:UNUSED_PAD src0_sel:WORD_1 src1_sel:DWORD
	v_add3_u32 v1, v6, v1, s65
	v_add3_u32 v0, v7, v0, s65
	v_and_b32_sdwa v6, v5, v209 dst_sel:DWORD dst_unused:UNUSED_PAD src0_sel:WORD_1 src1_sel:DWORD
	v_and_b32_sdwa v7, v4, v209 dst_sel:DWORD dst_unused:UNUSED_PAD src0_sel:WORD_1 src1_sel:DWORD
	v_add3_u32 v5, v5, v6, s65
	v_add3_u32 v4, v4, v7, s65
	v_readfirstlane_b32 s100, v253
	s_nop 0
	v_mov_b32_e32 v72, s100
	v_and_b32_e32 v72, 0x3fff, v72
	v_add_u32_e32 v72, s82, v72
	v_and_b32_e32 v5, 0xffff0000, v5
	v_and_b32_e32 v4, 0xffff0000, v4
	v_cmp_lt_i32_e32 vcc, s78, v72
	v_or_b32_sdwa v11, v5, v0 dst_sel:DWORD dst_unused:UNUSED_PAD src0_sel:DWORD src1_sel:WORD_1
	v_or_b32_sdwa v10, v4, v1 dst_sel:DWORD dst_unused:UNUSED_PAD src0_sel:DWORD src1_sel:WORD_1
	s_or_b64 s[86:87], vcc, s[86:87]
	s_cmp_lg_u64 s[88:89], 0
	s_cbranch_scc1 .Lxb_skip_3
	global_store_dwordx4 v[2:3], v[8:11], off offset:48
.Lxb_skip_3:
	s_andn2_b64 exec, exec, s[86:87]
	s_cbranch_execz .LBB0_1270

; __device__ __forceinline__ unsigned pack2(float a, float b) { return (unsigned)f2bf(a) | ((unsigned)f2bf(b) << 16); }
; __device__ void phase_peer(const Params& p, int l, float* xout, char* smem) {
;     ...
; #pragma unroll
;     for (int i = 0; i < 4; ++i) {
;       int c0 = lane * 32 + i * 8;
;       float o[8];
; #pragma unroll
;       for (int j = 0; j < 8; ++j) o[j] = (y[i * 8 + j] - mu) * rstd * g2[c0 + j] + b2[c0 + j];
;       if (xout) {
;         float* op = xout + (long)t * D_ + c0;
;         *(float4*)op = make_float4(o[0], o[1], o[2], o[3]);
;         *(float4*)(op + 4) = make_float4(o[4], o[5], o[6], o[7]);
;       }
;       uint4 pk; pk.x = pack2(o[0], o[1]); pk.y = pack2(o[2], o[3]); pk.z = pack2(o[4], o[5]); pk.w = pack2(o[6], o[7]);
;       *(uint4*)(p.xb + (long)t * D_ + c0) = pk;
;     }
.LBB0_1264:
	s_nop 1
	v_and_b32_sdwa v38, v37, v209 dst_sel:DWORD dst_unused:UNUSED_PAD src0_sel:WORD_1 src1_sel:DWORD
	v_and_b32_sdwa v39, v36, v209 dst_sel:DWORD dst_unused:UNUSED_PAD src0_sel:WORD_1 src1_sel:DWORD
	v_add3_u32 v36, v36, v39, s65
	v_add3_u32 v37, v37, v38, s65
	v_and_b32_sdwa v38, v31, v209 dst_sel:DWORD dst_unused:UNUSED_PAD src0_sel:WORD_1 src1_sel:DWORD
	v_and_b32_sdwa v39, v30, v209 dst_sel:DWORD dst_unused:UNUSED_PAD src0_sel:WORD_1 src1_sel:DWORD
	v_add3_u32 v31, v31, v38, s65
	v_add3_u32 v30, v30, v39, s65
	v_and_b32_e32 v31, 0xffff0000, v31
	v_and_b32_e32 v30, 0xffff0000, v30
	v_or_b32_sdwa v31, v31, v37 dst_sel:DWORD dst_unused:UNUSED_PAD src0_sel:DWORD src1_sel:WORD_1
	v_or_b32_sdwa v30, v30, v36 dst_sel:DWORD dst_unused:UNUSED_PAD src0_sel:DWORD src1_sel:WORD_1
	v_and_b32_sdwa v36, v35, v209 dst_sel:DWORD dst_unused:UNUSED_PAD src0_sel:WORD_1 src1_sel:DWORD
	v_and_b32_sdwa v37, v34, v209 dst_sel:DWORD dst_unused:UNUSED_PAD src0_sel:WORD_1 src1_sel:DWORD
	v_add3_u32 v34, v34, v37, s65
	v_add3_u32 v35, v35, v36, s65
	v_and_b32_sdwa v36, v33, v209 dst_sel:DWORD dst_unused:UNUSED_PAD src0_sel:WORD_1 src1_sel:DWORD
	v_and_b32_sdwa v37, v32, v209 dst_sel:DWORD dst_unused:UNUSED_PAD src0_sel:WORD_1 src1_sel:DWORD
	v_add3_u32 v33, v33, v36, s65
	v_add3_u32 v32, v32, v37, s65
	v_and_b32_e32 v33, 0xffff0000, v33
	v_and_b32_e32 v32, 0xffff0000, v32
	v_lshl_add_u64 v[2:3], v[90:91], 1, v[88:89]
	v_or_b32_sdwa v33, v33, v35 dst_sel:DWORD dst_unused:UNUSED_PAD src0_sel:DWORD src1_sel:WORD_1
	v_or_b32_sdwa v32, v32, v34 dst_sel:DWORD dst_unused:UNUSED_PAD src0_sel:DWORD src1_sel:WORD_1
	s_cmp_lg_u64 s[88:89], 0
	s_cbranch_scc1 .Lxb_skip_0
	global_store_dwordx4 v[2:3], v[30:33], off
.Lxb_skip_0:
	global_load_dwordx4 v[30:33], v[80:81], off offset:48
	s_nop 0
	global_load_dwordx4 v[34:37], v[80:81], off offset:32
	global_load_dwordx4 v[38:41], v[82:83], off offset:48
	global_load_dwordx4 v[42:45], v[82:83], off offset:32
	v_mov_b32_e32 v9, v8
	v_pk_mul_f32 v[24:25], v[24:25], v[8:9]
	v_pk_mul_f32 v[46:47], v[28:29], v[8:9]
	v_pk_mul_f32 v[22:23], v[22:23], v[8:9]
	s_andn2_b64 vcc, exec, s[88:89]
	s_waitcnt vmcnt(2)
	v_mov_b32_e32 v28, v34
	v_mov_b32_e32 v29, v36
	v_mov_b32_e32 v36, v35
	s_waitcnt vmcnt(0)
	v_mov_b32_e32 v34, v42
	v_mov_b32_e32 v35, v44
	v_pk_fma_f32 v[28:29], v[24:25], v[28:29], v[34:35]
	v_pk_mul_f32 v[34:35], v[26:27], v[8:9]
	v_mov_b32_e32 v26, v30
	v_mov_b32_e32 v27, v32
	v_mov_b32_e32 v32, v31
	v_mov_b32_e32 v30, v38
	v_mov_b32_e32 v31, v40
	v_mov_b32_e32 v44, v43
	v_pk_fma_f32 v[26:27], v[22:23], v[26:27], v[30:31]
	v_mov_b32_e32 v40, v39
	v_cndmask_b32_e64 v30, 0, 1, s[88:89]
	v_pk_fma_f32 v[24:25], v[46:47], v[36:37], v[44:45]
	v_pk_fma_f32 v[22:23], v[34:35], v[32:33], v[40:41]
	v_cmp_ne_u32_e64 s[40:41], 1, v30
	s_cbranch_vccnz .LBB0_1266
	v_lshl_add_u64 v[34:35], v[0:1], 0, v[176:177]
	v_mov_b32_e32 v30, v28
	v_mov_b32_e32 v31, v24
	v_mov_b32_e32 v32, v29
	v_mov_b32_e32 v33, v25
	global_store_dwordx4 v[34:35], v[30:33], off offset:32
	s_nop 1
	v_mov_b32_e32 v30, v26
	v_mov_b32_e32 v31, v22
	v_mov_b32_e32 v32, v27
	v_mov_b32_e32 v33, v23
	global_store_dwordx4 v[34:35], v[30:33], off offset:48
.LBB0_1266:
	s_nop 1
	v_and_b32_sdwa v30, v29, v209 dst_sel:DWORD dst_unused:UNUSED_PAD src0_sel:WORD_1 src1_sel:DWORD
	v_and_b32_sdwa v31, v28, v209 dst_sel:DWORD dst_unused:UNUSED_PAD src0_sel:WORD_1 src1_sel:DWORD
	v_add3_u32 v28, v28, v31, s65
	v_add3_u32 v29, v29, v30, s65
	v_and_b32_sdwa v30, v25, v209 dst_sel:DWORD dst_unused:UNUSED_PAD src0_sel:WORD_1 src1_sel:DWORD
	v_and_b32_sdwa v31, v24, v209 dst_sel:DWORD dst_unused:UNUSED_PAD src0_sel:WORD_1 src1_sel:DWORD
	v_add3_u32 v25, v25, v30, s65
	v_add3_u32 v24, v24, v31, s65
	v_and_b32_e32 v25, 0xffff0000, v25
	v_and_b32_e32 v24, 0xffff0000, v24
	v_or_b32_sdwa v25, v25, v29 dst_sel:DWORD dst_unused:UNUSED_PAD src0_sel:DWORD src1_sel:WORD_1
	v_or_b32_sdwa v24, v24, v28 dst_sel:DWORD dst_unused:UNUSED_PAD src0_sel:DWORD src1_sel:WORD_1
	v_and_b32_sdwa v28, v27, v209 dst_sel:DWORD dst_unused:UNUSED_PAD src0_sel:WORD_1 src1_sel:DWORD
	v_and_b32_sdwa v29, v26, v209 dst_sel:DWORD dst_unused:UNUSED_PAD src0_sel:WORD_1 src1_sel:DWORD
	v_add3_u32 v26, v26, v29, s65
	v_add3_u32 v27, v27, v28, s65
	v_and_b32_sdwa v28, v23, v209 dst_sel:DWORD dst_unused:UNUSED_PAD src0_sel:WORD_1 src1_sel:DWORD
	v_and_b32_sdwa v29, v22, v209 dst_sel:DWORD dst_unused:UNUSED_PAD src0_sel:WORD_1 src1_sel:DWORD
	v_add3_u32 v23, v23, v28, s65
	v_add3_u32 v22, v22, v29, s65
	v_and_b32_e32 v23, 0xffff0000, v23
	v_and_b32_e32 v22, 0xffff0000, v22
	v_or_b32_sdwa v27, v23, v27 dst_sel:DWORD dst_unused:UNUSED_PAD src0_sel:DWORD src1_sel:WORD_1
	v_or_b32_sdwa v26, v22, v26 dst_sel:DWORD dst_unused:UNUSED_PAD src0_sel:DWORD src1_sel:WORD_1
	s_cmp_lg_u64 s[88:89], 0
	s_cbranch_scc1 .Lxb_skip_1
	global_store_dwordx4 v[2:3], v[24:27], off offset:16
; __device__ __forceinline__ unsigned pack2(float a, float b) { return (unsigned)f2bf(a) | ((unsigned)f2bf(b) << 16); }
; __device__ void phase_peer(const Params& p, int l, float* xout, char* smem) {
;     ...
; #pragma unroll
;     for (int i = 0; i < 4; ++i) {
;       int c0 = lane * 32 + i * 8;
;       float o[8];
; #pragma unroll
;       for (int j = 0; j < 8; ++j) o[j] = (y[i * 8 + j] - mu) * rstd * g2[c0 + j] + b2[c0 + j];
;       if (xout) {
;         float* op = xout + (long)t * D_ + c0;
;         *(float4*)op = make_float4(o[0], o[1], o[2], o[3]);
;         *(float4*)(op + 4) = make_float4(o[4], o[5], o[6], o[7]);
;       }
;       uint4 pk; pk.x = pack2(o[0], o[1]); pk.y = pack2(o[2], o[3]); pk.z = pack2(o[4], o[5]); pk.w = pack2(o[6], o[7]);
;       *(uint4*)(p.xb + (long)t * D_ + c0) = pk;
;     }
.Lxb_skip_1:
	global_load_dwordx4 v[22:25], v[80:81], off offset:80
	s_nop 0
	global_load_dwordx4 v[26:29], v[80:81], off offset:64
	global_load_dwordx4 v[30:33], v[82:83], off offset:80
	global_load_dwordx4 v[34:37], v[82:83], off offset:64
	v_pk_mul_f32 v[18:19], v[18:19], v[8:9]
	v_pk_mul_f32 v[38:39], v[20:21], v[8:9]
	v_pk_mul_f32 v[14:15], v[14:15], v[8:9]
	s_and_b64 vcc, exec, s[40:41]
	s_waitcnt vmcnt(2)
	v_mov_b32_e32 v20, v26
	v_mov_b32_e32 v21, v28
	v_mov_b32_e32 v28, v27
	s_waitcnt vmcnt(0)
	v_mov_b32_e32 v26, v34
	v_mov_b32_e32 v27, v36
	v_pk_fma_f32 v[20:21], v[18:19], v[20:21], v[26:27]
	v_mov_b32_e32 v36, v35
	v_pk_mul_f32 v[26:27], v[16:17], v[8:9]
	v_mov_b32_e32 v16, v22
	v_mov_b32_e32 v17, v24
	v_mov_b32_e32 v24, v23
	v_mov_b32_e32 v22, v30
	v_mov_b32_e32 v23, v32
	v_mov_b32_e32 v32, v31
	v_pk_fma_f32 v[18:19], v[38:39], v[28:29], v[36:37]
	v_pk_fma_f32 v[16:17], v[14:15], v[16:17], v[22:23]
	v_pk_fma_f32 v[14:15], v[26:27], v[24:25], v[32:33]
	s_cbranch_vccnz .LBB0_1268
	v_lshl_add_u64 v[26:27], v[0:1], 0, v[176:177]
	v_mov_b32_e32 v22, v20
	v_mov_b32_e32 v23, v18
	v_mov_b32_e32 v24, v21
	v_mov_b32_e32 v25, v19
	global_store_dwordx4 v[26:27], v[22:25], off offset:64
	s_nop 1
	v_mov_b32_e32 v22, v16
	v_mov_b32_e32 v23, v14
	v_mov_b32_e32 v24, v17
	v_mov_b32_e32 v25, v15
	global_store_dwordx4 v[26:27], v[22:25], off offset:80
.LBB0_1268:
	s_nop 1
	v_and_b32_sdwa v22, v21, v209 dst_sel:DWORD dst_unused:UNUSED_PAD src0_sel:WORD_1 src1_sel:DWORD
	v_and_b32_sdwa v23, v20, v209 dst_sel:DWORD dst_unused:UNUSED_PAD src0_sel:WORD_1 src1_sel:DWORD
	v_add3_u32 v20, v20, v23, s65
	v_add3_u32 v21, v21, v22, s65
	v_and_b32_sdwa v22, v19, v209 dst_sel:DWORD dst_unused:UNUSED_PAD src0_sel:WORD_1 src1_sel:DWORD
	v_and_b32_sdwa v23, v18, v209 dst_sel:DWORD dst_unused:UNUSED_PAD src0_sel:WORD_1 src1_sel:DWORD
	v_add3_u32 v19, v19, v22, s65
	v_add3_u32 v18, v18, v23, s65
	v_and_b32_e32 v19, 0xffff0000, v19
	v_and_b32_e32 v18, 0xffff0000, v18
	v_or_b32_sdwa v19, v19, v21 dst_sel:DWORD dst_unused:UNUSED_PAD src0_sel:DWORD src1_sel:WORD_1
	v_or_b32_sdwa v18, v18, v20 dst_sel:DWORD dst_unused:UNUSED_PAD src0_sel:DWORD src1_sel:WORD_1
	v_and_b32_sdwa v20, v17, v209 dst_sel:DWORD dst_unused:UNUSED_PAD src0_sel:WORD_1 src1_sel:DWORD
	v_and_b32_sdwa v21, v16, v209 dst_sel:DWORD dst_unused:UNUSED_PAD src0_sel:WORD_1 src1_sel:DWORD
	v_add3_u32 v16, v16, v21, s65
	v_add3_u32 v17, v17, v20, s65
	v_and_b32_sdwa v20, v15, v209 dst_sel:DWORD dst_unused:UNUSED_PAD src0_sel:WORD_1 src1_sel:DWORD
	v_and_b32_sdwa v21, v14, v209 dst_sel:DWORD dst_unused:UNUSED_PAD src0_sel:WORD_1 src1_sel:DWORD
	v_add3_u32 v15, v15, v20, s65
	v_add3_u32 v14, v14, v21, s65
	v_and_b32_e32 v15, 0xffff0000, v15
	v_and_b32_e32 v14, 0xffff0000, v14
	v_or_b32_sdwa v21, v15, v17 dst_sel:DWORD dst_unused:UNUSED_PAD src0_sel:DWORD src1_sel:WORD_1
	v_or_b32_sdwa v20, v14, v16 dst_sel:DWORD dst_unused:UNUSED_PAD src0_sel:DWORD src1_sel:WORD_1
	s_cmp_lg_u64 s[88:89], 0
	s_cbranch_scc1 .Lxb_skip_2
	global_store_dwordx4 v[2:3], v[18:21], off offset:32
.Lxb_skip_2:
	global_load_dwordx4 v[14:17], v[80:81], off offset:112
	s_nop 0
	global_load_dwordx4 v[18:21], v[80:81], off offset:96
	global_load_dwordx4 v[22:25], v[82:83], off offset:112
	global_load_dwordx4 v[26:29], v[82:83], off offset:96
	v_pk_mul_f32 v[10:11], v[10:11], v[8:9]
	v_pk_mul_f32 v[30:31], v[12:13], v[8:9]
	v_pk_mul_f32 v[4:5], v[4:5], v[8:9]
	v_pk_mul_f32 v[8:9], v[6:7], v[8:9]
	s_and_b64 vcc, exec, s[40:41]
	s_waitcnt vmcnt(3)
	v_mov_b32_e32 v6, v14
	s_waitcnt vmcnt(2)
	v_mov_b32_e32 v12, v18
	v_mov_b32_e32 v13, v20
	v_mov_b32_e32 v20, v19
	s_waitcnt vmcnt(0)
	v_mov_b32_e32 v18, v26
	v_mov_b32_e32 v19, v28
	v_mov_b32_e32 v28, v27
	v_mov_b32_e32 v7, v16
	v_mov_b32_e32 v16, v15
	v_mov_b32_e32 v14, v22
	v_mov_b32_e32 v15, v24
	v_mov_b32_e32 v24, v23
	v_pk_fma_f32 v[12:13], v[10:11], v[12:13], v[18:19]
	v_pk_fma_f32 v[10:11], v[30:31], v[20:21], v[28:29]
	v_pk_fma_f32 v[6:7], v[4:5], v[6:7], v[14:15]
	v_pk_fma_f32 v[4:5], v[8:9], v[16:17], v[24:25]
	s_cbranch_vccnz .LBB0_1257
	v_lshl_add_u64 v[0:1], v[0:1], 0, v[176:177]
	v_mov_b32_e32 v14, v12
	v_mov_b32_e32 v15, v10
	v_mov_b32_e32 v16, v13
	v_mov_b32_e32 v17, v11
	global_store_dwordx4 v[0:1], v[14:17], off offset:96
	s_nop 1
	v_mov_b32_e32 v14, v6
	v_mov_b32_e32 v15, v4
	v_mov_b32_e32 v16, v7
	v_mov_b32_e32 v17, v5
	global_store_dwordx4 v[0:1], v[14:17], off offset:112
	s_branch .LBB0_1257
